# record-builder prefetch loads moved behind the first barrier of the iteration so no wait of the current iteration covers them
# speedup vs baseline: 1.0079x; 1.0079x over previous
.Lr1_nopf:
	global_load_dwordx4 v[8:11], v[4:5], off
	global_load_dwordx4 v[76:79], v[12:13], off
	global_load_dwordx4 v[32:35], v[12:13], off offset:1024
	global_load_dwordx4 v[36:39], v[2:3], off offset:1024
	global_load_dwordx4 v[24:27], v[2:3], off offset:2048
	s_load_dwordx2 s[4:5], s[18:19], 0xb0
	v_lshlrev_b32_e32 v156, 2, v14
	global_load_dwordx4 v[80:83], v[0:1], off
	global_load_dwordx4 v[28:31], v[12:13], off offset:2048
	global_load_dwordx4 v[72:75], v[6:7], off offset:1024
	s_nop 0
	global_load_dwordx4 v[0:3], v[6:7], off offset:2048
	s_waitcnt lgkmcnt(0)
	global_load_dwordx4 v[52:55], v156, s[4:5] offset:16
	global_load_dwordx4 v[56:59], v156, s[4:5]
	global_load_dwordx4 v[40:43], v156, s[4:5] offset:2064
	global_load_dwordx4 v[48:51], v156, s[4:5] offset:2048
	v_lshl_add_u64 v[4:5], s[4:5], 0, v[156:157]
	v_lshl_add_u64 v[6:7], v[4:5], 0, s[46:47]
	v_add_co_u32_e32 v4, vcc, 0x1000, v4
	v_cmp_le_u32_e64 s[4:5], s7, v109
	s_nop 0
	v_addc_co_u32_e32 v5, vcc, 0, v5, vcc
	global_load_dwordx4 v[12:15], v[4:5], off
	s_nop 0
	global_load_dwordx4 v[4:7], v[6:7], off offset:16
	s_and_b64 s[14:15], s[12:13], s[2:3]
	v_mov_b32_e32 v60, 0
	v_mov_b32_e32 v61, 0
	v_mov_b32_e32 v62, 0
	v_mov_b32_e32 v63, 0
	v_mov_b32_e32 v64, 0
	v_mov_b32_e32 v65, 0
	v_mov_b32_e32 v66, 0
	v_mov_b32_e32 v67, 0
	v_mov_b32_e32 v68, 0
	v_mov_b32_e32 v69, 0
	v_mov_b32_e32 v70, 0
	v_mov_b32_e32 v71, 0
	v_mov_b32_e32 v44, 0
	v_mov_b32_e32 v45, 0
	v_mov_b32_e32 v46, 0
	v_mov_b32_e32 v47, 0
	v_mov_b32_e32 v20, 0
	v_mov_b32_e32 v21, 0
	v_mov_b32_e32 v22, 0
	v_mov_b32_e32 v23, 0
	v_mov_b32_e32 v16, 0
	v_mov_b32_e32 v17, 0
	v_mov_b32_e32 v18, 0
	v_mov_b32_e32 v19, 0
	s_and_saveexec_b64 s[12:13], s[14:15]
	s_cbranch_execz .LBB0_328
	s_load_dwordx2 s[14:15], s[18:19], 0x30
	s_mul_hi_i32 s7, s1, 0x1c00
	s_mulk_i32 s1, 0x1c00
	s_waitcnt lgkmcnt(0)
	s_add_u32 s14, s14, s1
	s_addc_u32 s15, s15, s7
	v_lshl_add_u64 v[16:17], s[14:15], 0, v[156:157]
	global_load_dwordx4 v[60:63], v156, s[14:15]
	global_load_dwordx4 v[64:67], v156, s[14:15] offset:16
	global_load_dwordx4 v[68:71], v156, s[14:15] offset:2048
	global_load_dwordx4 v[44:47], v156, s[14:15] offset:2064
	v_lshl_add_u64 v[18:19], v[16:17], 0, s[46:47]
	v_add_co_u32_e32 v16, vcc, 0x1000, v16
	s_nop 1
	v_addc_co_u32_e32 v17, vcc, 0, v17, vcc
	global_load_dwordx4 v[20:23], v[16:17], off
	s_nop 0
	global_load_dwordx4 v[16:19], v[18:19], off offset:16

.LBB0_332:
	s_or_b64 exec, exec, s[12:13]
	s_mul_i32 s0, s0, 0x8800
	s_add_i32 s16, s0, 0
	s_mul_i32 s1, s6, 0x4800
	s_mul_hi_i32 s0, s6, 0x4800
	s_add_u32 s1, s10, s1
	s_addc_u32 s0, s11, s0
	v_mul_u32_u24_e32 v0, 0x44, v109
	s_add_u32 s12, s1, 0x2a600000
	v_and_b32_e32 v16, 0x7f, v108
	v_lshlrev_b32_e32 v0, 2, v0
	s_addc_u32 s13, s0, 0
	v_add3_u32 v0, s16, v0, v88
	v_lshlrev_b32_e32 v1, 2, v118
	v_cmp_gt_u32_e32 vcc, 64, v16
	v_add3_u32 v1, s16, v1, v88
	ds_write_b128 v0, v[72:75]
	ds_write_b128 v1, v[52:55] offset:17408
	ds_write_b128 v0, v[76:79] offset:4352
	ds_write_b128 v0, v[40:43] offset:8704
	ds_write_b128 v0, v[44:47] offset:13056
	ds_write_b128 v1, v[56:59] offset:28160
	ds_write_b128 v0, v[64:67] offset:16
	ds_write_b128 v1, v[48:51] offset:17424
	ds_write_b128 v0, v[68:71] offset:4368
	ds_write_b128 v0, v[32:35] offset:8720
	ds_write_b128 v0, v[36:39] offset:13072
	ds_write_b128 v1, v[60:63] offset:28176
	s_waitcnt lgkmcnt(0)
	s_barrier
	s_cmpk_lt_i32 s6, 0x1c00
	s_cbranch_scc0 .Lr1_nopf2
	global_load_dwordx4 v[170:173], v[160:161], off
	global_load_dwordx4 v[170:173], v[160:161], off offset:1024
	global_load_dwordx4 v[170:173], v[160:161], off offset:2048
	global_load_dwordx4 v[170:173], v[162:163], off
	global_load_dwordx4 v[170:173], v[162:163], off offset:1024
	global_load_dwordx4 v[170:173], v[162:163], off offset:2048
	global_load_dwordx4 v[170:173], v[164:165], off
	global_load_dwordx4 v[170:173], v[164:165], off offset:1024
	global_load_dwordx4 v[170:173], v[164:165], off offset:2048
.Lr1_nopf2:
	s_and_saveexec_b64 s[2:3], vcc
	s_cbranch_execz .LBB0_334
	v_lshlrev_b32_e32 v156, 2, v16
	v_add_u32_e32 v4, s16, v156
	v_add_u32_e32 v0, 0x4200, v4
	ds_read2_b32 v[0:1], v0 offset0:60 offset1:128
	v_add_u32_e32 v5, 0x3000, v4
	v_add_u32_e32 v17, 0x1000, v4
	ds_read2_b32 v[2:3], v5 offset0:124 offset1:192
	v_add_u32_e32 v27, 0x2200, v4
	s_waitcnt lgkmcnt(1)
	v_div_scale_f32 v6, s[0:1], v1, v1, 1.0
	v_rcp_f32_e32 v7, v6
	v_div_scale_f32 v8, vcc, 1.0, v1, 1.0
	v_add_u32_e32 v28, 0x3400, v4
	v_fma_f32 v9, -v6, v7, 1.0
	v_fmac_f32_e32 v7, v9, v7
	v_mul_f32_e32 v9, v8, v7
	v_fma_f32 v10, -v6, v9, v8
	v_fmac_f32_e32 v9, v10, v7
	v_fma_f32 v6, -v6, v9, v8
	v_div_fmas_f32 v6, v6, v7, v9
	v_div_fixup_f32 v20, v6, v1, 1.0
	ds_read2_b32 v[6:7], v17 offset0:64 offset1:132
	ds_read2st64_b32 v[8:9], v4 offset0:69 offset1:70
	ds_read2_b32 v[10:11], v4 offset1:68
	ds_read2st64_b32 v[12:13], v4 offset0:71 offset1:72
	ds_read2st64_b32 v[14:15], v4 offset0:73 offset1:74
	ds_read2st64_b32 v[18:19], v4 offset0:75 offset1:76
	s_waitcnt lgkmcnt(4)
	v_mul_f32_e32 v8, v1, v8
	v_div_scale_f32 v21, s[0:1], v8, v8, 1.0
	v_rcp_f32_e32 v24, v21
	v_mul_f32_e32 v3, v20, v3
	v_mul_f32_e32 v6, v20, v6
	s_waitcnt lgkmcnt(3)
	v_mul_f32_e32 v10, v1, v10
	v_fma_f32 v20, -v21, v24, 1.0
	v_fmac_f32_e32 v24, v20, v24
	v_div_scale_f32 v20, vcc, 1.0, v8, 1.0
	v_mul_f32_e32 v25, v20, v24
	v_fma_f32 v22, -v21, v25, v20
	v_fmac_f32_e32 v25, v22, v24
	v_fma_f32 v26, -v21, v25, v20
	ds_read2_b32 v[20:21], v27 offset0:68 offset1:136
	ds_read2_b32 v[22:23], v28 offset0:4 offset1:72
	v_div_fmas_f32 v24, v26, v24, v25
	v_div_fixup_f32 v24, v24, v8, 1.0
	v_mul_f32_e32 v7, v24, v7
	s_waitcnt lgkmcnt(1)
	v_mul_f32_e32 v1, v1, v20
	s_waitcnt lgkmcnt(0)
	v_mul_f32_e32 v20, v24, v22
	v_mul_f32_e32 v22, v8, v9
	v_div_scale_f32 v9, s[0:1], v22, v22, 1.0
	v_rcp_f32_e32 v24, v9
	ds_write2_b32 v17, v6, v7 offset0:64 offset1:132
	v_mul_f32_e32 v6, v8, v11
	ds_write2_b32 v4, v10, v6 offset1:68
	v_fma_f32 v6, -v9, v24, 1.0
	v_fmac_f32_e32 v24, v6, v24
	v_div_scale_f32 v6, vcc, 1.0, v22, 1.0
	v_mul_f32_e32 v7, v6, v24
	v_fma_f32 v10, -v9, v7, v6
	v_fmac_f32_e32 v7, v10, v24
	v_fma_f32 v6, -v9, v7, v6
	v_div_fmas_f32 v6, v6, v24, v7
	v_div_fixup_f32 v10, v6, v22, 1.0
	v_mul_f32_e32 v6, v8, v21
	ds_write2_b32 v27, v1, v6 offset0:68 offset1:136
	v_add_u32_e32 v17, 0x1200, v4
	v_mul_f32_e32 v12, v22, v12
	ds_read2_b32 v[6:7], v17 offset0:72 offset1:140
	ds_read2_b32 v[8:9], v4 offset0:136 offset1:204
	v_div_scale_f32 v11, s[0:1], v12, v12, 1.0
	v_mul_f32_e32 v1, v10, v23
	v_rcp_f32_e32 v23, v11
	ds_write2_b32 v28, v20, v1 offset0:4 offset1:72
	s_waitcnt lgkmcnt(2)
	v_mul_f32_e32 v1, v10, v6
	s_waitcnt lgkmcnt(1)
	v_mul_f32_e32 v6, v22, v8
	v_fma_f32 v8, -v11, v23, 1.0
	v_fmac_f32_e32 v23, v8, v23
	v_div_scale_f32 v8, vcc, 1.0, v12, 1.0
	v_mul_f32_e32 v24, v8, v23
	v_fma_f32 v10, -v11, v24, v8
	v_fmac_f32_e32 v24, v10, v23
	v_add_u32_e32 v25, 0x2400, v4
	v_fma_f32 v8, -v11, v24, v8
	ds_read2_b32 v[10:11], v25 offset0:76 offset1:144
	ds_read2_b32 v[20:21], v28 offset0:140 offset1:208
	v_div_fmas_f32 v8, v8, v23, v24
	v_div_fixup_f32 v8, v8, v12, 1.0
	v_mul_f32_e32 v7, v8, v7
	s_waitcnt lgkmcnt(1)
	v_mul_f32_e32 v10, v22, v10
	v_mul_f32_e32 v22, v12, v13
	s_waitcnt lgkmcnt(0)
	v_mul_f32_e32 v20, v8, v20
	v_div_scale_f32 v8, s[0:1], v22, v22, 1.0
	v_rcp_f32_e32 v13, v8
	ds_write2_b32 v17, v1, v7 offset0:72 offset1:140
	v_mul_f32_e32 v1, v12, v9
	ds_write2_b32 v4, v6, v1 offset0:136 offset1:204
	v_fma_f32 v1, -v8, v13, 1.0
	v_fmac_f32_e32 v13, v1, v13
	v_div_scale_f32 v1, vcc, 1.0, v22, 1.0
	v_mul_f32_e32 v6, v1, v13
	v_fma_f32 v7, -v8, v6, v1
	v_fmac_f32_e32 v6, v7, v13
	v_fma_f32 v1, -v8, v6, v1
	v_div_fmas_f32 v1, v1, v13, v6
	v_div_fixup_f32 v1, v1, v22, 1.0
	v_mul_f32_e32 v6, v12, v11
	ds_write2_b32 v25, v10, v6 offset0:76 offset1:144
	v_mul_f32_e32 v10, v1, v21
	v_add_u32_e32 v17, 0x1400, v4
	v_add_u32_e32 v21, 0x400, v4
	v_mul_f32_e32 v14, v22, v14
	ds_read2_b32 v[6:7], v17 offset0:80 offset1:148
	ds_read2_b32 v[8:9], v21 offset0:16 offset1:84
	v_div_scale_f32 v11, s[0:1], v14, v14, 1.0
	v_rcp_f32_e32 v23, v11
	s_waitcnt lgkmcnt(1)
	v_mul_f32_e32 v1, v1, v6
	s_waitcnt lgkmcnt(0)
	v_mul_f32_e32 v6, v22, v8
	ds_write2_b32 v28, v20, v10 offset0:140 offset1:208
	v_fma_f32 v8, -v11, v23, 1.0
	v_fmac_f32_e32 v23, v8, v23
	v_div_scale_f32 v8, vcc, 1.0, v14, 1.0
	v_mul_f32_e32 v20, v8, v23
	v_add_u32_e32 v25, 0x3800, v4
	v_fma_f32 v10, -v11, v20, v8
	ds_read2_b32 v[12:13], v25 offset0:20 offset1:88
	v_fmac_f32_e32 v20, v10, v23
	v_fma_f32 v8, -v11, v20, v8
	v_div_fmas_f32 v8, v8, v23, v20
	v_div_fixup_f32 v8, v8, v14, 1.0
	v_mul_f32_e32 v15, v14, v15
	s_waitcnt lgkmcnt(0)
	v_mul_f32_e32 v12, v8, v12
	v_mul_f32_e32 v7, v8, v7
	v_div_scale_f32 v8, s[0:1], v15, v15, 1.0
	v_rcp_f32_e32 v20, v8
	ds_write2_b32 v17, v1, v7 offset0:80 offset1:148
	v_mul_f32_e32 v1, v14, v9
	v_add_u32_e32 v24, 0x2600, v4
	ds_write2_b32 v21, v6, v1 offset0:16 offset1:84
	v_fma_f32 v1, -v8, v20, 1.0
	ds_read2_b32 v[10:11], v24 offset0:84 offset1:152
	v_fmac_f32_e32 v20, v1, v20
	v_div_scale_f32 v1, vcc, 1.0, v15, 1.0
	v_mul_f32_e32 v6, v1, v20
	v_fma_f32 v7, -v8, v6, v1
	v_fmac_f32_e32 v6, v7, v20
	v_fma_f32 v1, -v8, v6, v1
	s_waitcnt lgkmcnt(0)
	v_mul_f32_e32 v10, v22, v10
	v_div_fmas_f32 v1, v1, v20, v6
	v_mul_f32_e32 v6, v14, v11
	ds_write2_b32 v24, v10, v6 offset0:84 offset1:152
	v_add_u32_e32 v14, 0x1600, v4
	v_mul_f32_e32 v17, v15, v18
	ds_read2_b32 v[6:7], v14 offset0:88 offset1:156
	ds_read2_b32 v[8:9], v21 offset0:152 offset1:220
	v_div_scale_f32 v11, s[0:1], v17, v17, 1.0
	v_rcp_f32_e32 v18, v11
	v_div_fixup_f32 v1, v1, v15, 1.0
	v_mul_f32_e32 v10, v1, v13
	s_waitcnt lgkmcnt(1)
	v_mul_f32_e32 v1, v1, v6
	s_waitcnt lgkmcnt(0)
	v_mul_f32_e32 v6, v15, v8
	v_fma_f32 v8, -v11, v18, 1.0
	v_fmac_f32_e32 v18, v8, v18
	v_div_scale_f32 v8, vcc, 1.0, v17, 1.0
	v_mul_f32_e32 v20, v8, v18
	ds_write2_b32 v25, v12, v10 offset0:20 offset1:88
	v_fma_f32 v10, -v11, v20, v8
	v_fmac_f32_e32 v20, v10, v18
	v_add_u32_e32 v22, 0x2800, v4
	v_fma_f32 v8, -v11, v20, v8
	ds_read2_b32 v[10:11], v22 offset0:92 offset1:160
	ds_read2_b32 v[12:13], v25 offset0:156 offset1:224
	v_div_fmas_f32 v8, v8, v18, v20
	v_div_fixup_f32 v8, v8, v17, 1.0
	v_mul_f32_e32 v23, v17, v19
	v_mul_f32_e32 v7, v8, v7
	s_waitcnt lgkmcnt(0)
	v_mul_f32_e32 v18, v8, v12
	v_div_scale_f32 v8, s[0:1], v23, v23, 1.0
	v_rcp_f32_e32 v12, v8
	ds_write2_b32 v14, v1, v7 offset0:88 offset1:156
	v_mul_f32_e32 v1, v17, v9
	ds_write2_b32 v21, v6, v1 offset0:152 offset1:220
	v_fma_f32 v1, -v8, v12, 1.0
	v_fmac_f32_e32 v12, v1, v12
	v_div_scale_f32 v1, vcc, 1.0, v23, 1.0
	v_mul_f32_e32 v6, v1, v12
	v_fma_f32 v7, -v8, v6, v1
	v_fmac_f32_e32 v6, v7, v12
	v_fma_f32 v1, -v8, v6, v1
	v_mul_f32_e32 v10, v15, v10
	v_div_fmas_f32 v1, v1, v12, v6
	v_mul_f32_e32 v6, v17, v11
	v_div_fixup_f32 v1, v1, v23, 1.0
	ds_write2_b32 v22, v10, v6 offset0:92 offset1:160
	v_add_u32_e32 v22, 0x1800, v4
	v_mul_f32_e32 v17, v1, v13
	ds_read2_b32 v[6:7], v22 offset0:96 offset1:164
	v_add_u32_e32 v24, 0x800, v4
	ds_read2st64_b32 v[8:9], v4 offset0:77 offset1:78
	ds_read2_b32 v[10:11], v24 offset0:32 offset1:100
	ds_read2st64_b32 v[12:13], v4 offset0:79 offset1:80
	ds_read2st64_b32 v[14:15], v4 offset0:81 offset1:82
	ds_read_b32 v26, v4 offset:21248
	s_waitcnt lgkmcnt(4)
	v_mul_f32_e32 v8, v23, v8
	v_div_scale_f32 v19, s[0:1], v8, v8, 1.0
	v_rcp_f32_e32 v27, v19
	v_mul_f32_e32 v1, v1, v6
	s_waitcnt lgkmcnt(3)
	v_mul_f32_e32 v6, v23, v10
	ds_write2_b32 v25, v18, v17 offset0:156 offset1:224
	v_fma_f32 v10, -v19, v27, 1.0
	v_fmac_f32_e32 v27, v10, v27
	v_div_scale_f32 v10, vcc, 1.0, v8, 1.0
	v_mul_f32_e32 v17, v10, v27
	v_fma_f32 v18, -v19, v17, v10
	v_fmac_f32_e32 v17, v18, v27
	v_add_u32_e32 v25, 0x2a00, v4
	v_add_u32_e32 v28, 0x3c00, v4
	v_fma_f32 v10, -v19, v17, v10
	ds_read2_b32 v[18:19], v25 offset0:100 offset1:168
	ds_read2_b32 v[20:21], v28 offset0:36 offset1:104
	v_div_fmas_f32 v10, v10, v27, v17
	v_div_fixup_f32 v10, v10, v8, 1.0
	v_mul_f32_e32 v7, v10, v7
	s_waitcnt lgkmcnt(1)
	v_mul_f32_e32 v17, v23, v18
	s_waitcnt lgkmcnt(0)
	v_mul_f32_e32 v18, v10, v20
	v_mul_f32_e32 v20, v8, v9
	v_div_scale_f32 v9, s[0:1], v20, v20, 1.0
	v_rcp_f32_e32 v10, v9
	ds_write2_b32 v22, v1, v7 offset0:96 offset1:164
	v_mul_f32_e32 v1, v8, v11
	ds_write2_b32 v24, v6, v1 offset0:32 offset1:100
	v_fma_f32 v1, -v9, v10, 1.0
	v_fmac_f32_e32 v10, v1, v10
	v_div_scale_f32 v1, vcc, 1.0, v20, 1.0
	v_mul_f32_e32 v6, v1, v10
	v_fma_f32 v7, -v9, v6, v1
	v_fmac_f32_e32 v6, v7, v10
	v_fma_f32 v1, -v9, v6, v1
	v_div_fmas_f32 v1, v1, v10, v6
	v_mul_f32_e32 v6, v8, v19
	ds_write2_b32 v25, v17, v6 offset0:100 offset1:168
	v_add_u32_e32 v17, 0x1a00, v4
	v_mul_f32_e32 v12, v20, v12
	v_div_fixup_f32 v1, v1, v20, 1.0
	ds_read2_b32 v[6:7], v17 offset0:104 offset1:172
	ds_read2_b32 v[8:9], v24 offset0:168 offset1:236
	v_div_scale_f32 v11, s[0:1], v12, v12, 1.0
	v_mul_f32_e32 v10, v1, v21
	v_rcp_f32_e32 v21, v11
	s_waitcnt lgkmcnt(1)
	v_mul_f32_e32 v1, v1, v6
	s_waitcnt lgkmcnt(0)
	v_mul_f32_e32 v6, v20, v8
	ds_write2_b32 v28, v18, v10 offset0:36 offset1:104
	v_fma_f32 v8, -v11, v21, 1.0
	v_fmac_f32_e32 v21, v8, v21
	v_div_scale_f32 v8, vcc, 1.0, v12, 1.0
	v_mul_f32_e32 v22, v8, v21
	v_fma_f32 v10, -v11, v22, v8
	v_fmac_f32_e32 v22, v10, v21
	v_add_u32_e32 v23, 0x2c00, v4
	v_fma_f32 v8, -v11, v22, v8
	ds_read2_b32 v[10:11], v23 offset0:108 offset1:176
	ds_read2_b32 v[18:19], v28 offset0:172 offset1:240
	v_div_fmas_f32 v8, v8, v21, v22
	v_div_fixup_f32 v8, v8, v12, 1.0
	v_mul_f32_e32 v7, v8, v7
	s_waitcnt lgkmcnt(1)
	v_mul_f32_e32 v10, v20, v10
	v_mul_f32_e32 v20, v12, v13
	s_waitcnt lgkmcnt(0)
	v_mul_f32_e32 v18, v8, v18
	v_div_scale_f32 v8, s[0:1], v20, v20, 1.0
	v_rcp_f32_e32 v13, v8
	ds_write2_b32 v17, v1, v7 offset0:104 offset1:172
	v_mul_f32_e32 v1, v12, v9
	ds_write2_b32 v24, v6, v1 offset0:168 offset1:236
	v_fma_f32 v1, -v8, v13, 1.0
	v_fmac_f32_e32 v13, v1, v13
	v_div_scale_f32 v1, vcc, 1.0, v20, 1.0
	v_mul_f32_e32 v6, v1, v13
	v_fma_f32 v7, -v8, v6, v1
	v_fmac_f32_e32 v6, v7, v13
	v_fma_f32 v1, -v8, v6, v1
	v_div_fmas_f32 v1, v1, v13, v6
	v_div_fixup_f32 v1, v1, v20, 1.0
	v_mul_f32_e32 v6, v12, v11
	ds_write2_b32 v23, v10, v6 offset0:108 offset1:176
	v_mul_f32_e32 v10, v1, v19
	v_add_u32_e32 v17, 0x1c00, v4
	v_add_u32_e32 v19, 0xc00, v4
	v_mul_f32_e32 v14, v20, v14
	ds_read2_b32 v[6:7], v17 offset0:112 offset1:180
	ds_read2_b32 v[8:9], v19 offset0:48 offset1:116
	v_div_scale_f32 v11, s[0:1], v14, v14, 1.0
	v_rcp_f32_e32 v21, v11
	s_waitcnt lgkmcnt(1)
	v_mul_f32_e32 v1, v1, v6
	s_waitcnt lgkmcnt(0)
	v_mul_f32_e32 v6, v20, v8
	ds_write2_b32 v28, v18, v10 offset0:172 offset1:240
	v_fma_f32 v8, -v11, v21, 1.0
	v_fmac_f32_e32 v21, v8, v21
	v_div_scale_f32 v8, vcc, 1.0, v14, 1.0
	v_mul_f32_e32 v18, v8, v21
	v_add_u32_e32 v23, 0x4000, v4
	v_fma_f32 v10, -v11, v18, v8
	ds_read2_b32 v[12:13], v23 offset0:52 offset1:120
	v_fmac_f32_e32 v18, v10, v21
	v_fma_f32 v8, -v11, v18, v8
	v_div_fmas_f32 v8, v8, v21, v18
	v_div_fixup_f32 v8, v8, v14, 1.0
	v_mul_f32_e32 v15, v14, v15
	s_waitcnt lgkmcnt(0)
	v_mul_f32_e32 v12, v8, v12
	v_mul_f32_e32 v7, v8, v7
	v_div_scale_f32 v8, s[0:1], v15, v15, 1.0
	v_rcp_f32_e32 v18, v8
	ds_write2_b32 v17, v1, v7 offset0:112 offset1:180
	v_mul_f32_e32 v1, v14, v9
	ds_write2_b32 v19, v6, v1 offset0:48 offset1:116
	v_fma_f32 v1, -v8, v18, 1.0
	v_add_u32_e32 v22, 0x2e00, v4
	v_fmac_f32_e32 v18, v1, v18
	v_div_scale_f32 v1, vcc, 1.0, v15, 1.0
	ds_read2_b32 v[10:11], v22 offset0:116 offset1:184
	v_mul_f32_e32 v6, v1, v18
	v_fma_f32 v7, -v8, v6, v1
	v_fmac_f32_e32 v6, v7, v18
	v_fma_f32 v1, -v8, v6, v1
	v_div_fmas_f32 v1, v1, v18, v6
	s_waitcnt lgkmcnt(0)
	v_mul_f32_e32 v10, v20, v10
	v_div_fixup_f32 v1, v1, v15, 1.0
	v_mul_f32_e32 v6, v14, v11
	ds_write2_b32 v22, v10, v6 offset0:116 offset1:184
	v_mul_f32_e32 v10, v1, v13
	v_add_u32_e32 v11, 0x1e00, v4
	v_mul_f32_e32 v13, v15, v26
	ds_read2_b32 v[6:7], v11 offset0:120 offset1:188
	ds_read2_b32 v[8:9], v19 offset0:184 offset1:252
	v_div_scale_f32 v14, s[0:1], v13, v13, 1.0
	v_rcp_f32_e32 v17, v14
	s_waitcnt lgkmcnt(1)
	v_mul_f32_e32 v1, v1, v6
	s_waitcnt lgkmcnt(0)
	v_mul_f32_e32 v6, v15, v8
	ds_write2_b32 v23, v12, v10 offset0:52 offset1:120
	v_fma_f32 v8, -v14, v17, 1.0
	v_fmac_f32_e32 v17, v8, v17
	v_div_scale_f32 v8, vcc, 1.0, v13, 1.0
	v_mul_f32_e32 v10, v8, v17
	v_fma_f32 v12, -v14, v10, v8
	v_fmac_f32_e32 v10, v12, v17
	v_fma_f32 v8, -v14, v10, v8
	v_div_fmas_f32 v8, v8, v17, v10
	v_div_fixup_f32 v8, v8, v13, 1.0
	v_mul_f32_e32 v0, v8, v0
	ds_write_b32 v4, v0 offset:17136
	v_mul_f32_e32 v0, v8, v7
	v_mul_f32_e32 v2, v15, v2
	ds_write2_b32 v11, v1, v0 offset0:120 offset1:188
	v_mul_f32_e32 v0, v13, v9
	ds_write2_b32 v5, v2, v3 offset0:124 offset1:192
	ds_write2_b32 v19, v6, v0 offset0:184 offset1:252
	ds_write_b32 v4, v13 offset:27904
	v_lshl_add_u64 v[0:1], s[12:13], 0, v[156:157]
	v_add_co_u32_e32 v0, vcc, 0x4000, v0
	s_nop 1
	v_addc_co_u32_e32 v1, vcc, 0, v1, vcc
	global_store_dword v[0:1], v13, off offset:1408
